# P1 K_SILU tile epilogues (two copies) replaced by one hand-written body: packed f32 mul/add, no s_nop between transcendental and use, stores deferred one group behind their bpermutes
# speedup vs baseline: 1.0054x; 1.0030x over previous
.LBB0_145:
	v_lshl_add_u32 v135, v150, 4, v3
	v_and_b32_e32 v134, 15, v3
	v_and_b32_e32 v137, 3, v3
	v_sub_u32_e32 v134, v5, v134
	v_ashrrev_i32_e32 v136, 2, v135
	v_lshlrev_b32_e32 v138, 3, v137
	v_lshlrev_b32_e32 v137, 6, v137
	v_add_u32_e32 v134, v136, v134
	v_ashrrev_i32_e32 v136, 1, v135
	v_and_or_b32 v151, v135, -4, v137
	s_lshl_b32 s0, s72, 8
	s_addk_i32 s0, 0xea00
	v_and_b32_e32 v136, -8, v136
	v_add3_u32 v138, s0, v4, v138
	v_sub_u32_e32 v136, v138, v136
	v_readlane_b32 s0, v254, 49
	v_readlane_b32 s1, v254, 50
	v_ashrrev_i32_e32 v137, 31, v136
	v_ashrrev_i32_e32 v135, 31, v134
	v_lshlrev_b64 v[134:135], 11, v[134:135]
	v_lshl_add_u64 v[136:137], v[136:137], 1, s[0:1]
	v_lshl_add_u64 v[136:137], v[136:137], 0, v[134:135]
.Lsilu_body:
	s_mov_b32 s84, 0xbfb8aa3b
	s_mov_b32 s85, s84
	s_mov_b32 s86, 1.0
	s_mov_b32 s87, 1.0
	v_mov_b64_e32 v[138:139], v[136:137]
	v_pk_mul_f32 v[152:153], v[102:103], s[84:85] op_sel_hi:[1,0]
	v_pk_mul_f32 v[154:155], v[104:105], s[84:85] op_sel_hi:[1,0]
	v_pk_mul_f32 v[156:157], v[70:71], s[84:85] op_sel_hi:[1,0]
	v_pk_mul_f32 v[158:159], v[72:73], s[84:85] op_sel_hi:[1,0]
	v_exp_f32_e32 v152, v152
	v_exp_f32_e32 v153, v153
	v_exp_f32_e32 v154, v154
	v_exp_f32_e32 v155, v155
	v_exp_f32_e32 v156, v156
	v_exp_f32_e32 v157, v157
	v_exp_f32_e32 v158, v158
	v_exp_f32_e32 v159, v159
	v_pk_add_f32 v[152:153], v[152:153], s[86:87] op_sel_hi:[1,0]
	v_pk_add_f32 v[154:155], v[154:155], s[86:87] op_sel_hi:[1,0]
	v_pk_add_f32 v[156:157], v[156:157], s[86:87] op_sel_hi:[1,0]
	v_pk_add_f32 v[158:159], v[158:159], s[86:87] op_sel_hi:[1,0]
	v_rcp_f32_e32 v152, v152
	v_rcp_f32_e32 v153, v153
	v_rcp_f32_e32 v154, v154
	v_rcp_f32_e32 v155, v155
	v_rcp_f32_e32 v156, v156
	v_rcp_f32_e32 v157, v157
	v_rcp_f32_e32 v158, v158
	v_rcp_f32_e32 v159, v159
	v_pk_mul_f32 v[152:153], v[102:103], v[152:153]
	v_pk_mul_f32 v[154:155], v[104:105], v[154:155]
	v_pk_mul_f32 v[156:157], v[70:71], v[156:157]
	v_pk_mul_f32 v[158:159], v[72:73], v[158:159]
	v_cvt_pk_bf16_f32 v160, v152, v153
	v_cvt_pk_bf16_f32 v161, v154, v155
	v_cvt_pk_bf16_f32 v162, v156, v157
	v_cvt_pk_bf16_f32 v163, v158, v159
	ds_bpermute_b32 v164, v151, v160
	ds_bpermute_b32 v165, v151, v161
	ds_bpermute_b32 v166, v151, v162
	ds_bpermute_b32 v167, v151, v163
	v_pk_mul_f32 v[168:169], v[130:131], s[84:85] op_sel_hi:[1,0]
	v_pk_mul_f32 v[170:171], v[132:133], s[84:85] op_sel_hi:[1,0]
	v_pk_mul_f32 v[172:173], v[98:99], s[84:85] op_sel_hi:[1,0]
	v_pk_mul_f32 v[174:175], v[100:101], s[84:85] op_sel_hi:[1,0]
	v_exp_f32_e32 v168, v168
	v_exp_f32_e32 v169, v169
	v_exp_f32_e32 v170, v170
	v_exp_f32_e32 v171, v171
	v_exp_f32_e32 v172, v172
	v_exp_f32_e32 v173, v173
	v_exp_f32_e32 v174, v174
	v_exp_f32_e32 v175, v175
	v_pk_add_f32 v[168:169], v[168:169], s[86:87] op_sel_hi:[1,0]
	v_pk_add_f32 v[170:171], v[170:171], s[86:87] op_sel_hi:[1,0]
	v_pk_add_f32 v[172:173], v[172:173], s[86:87] op_sel_hi:[1,0]
	v_pk_add_f32 v[174:175], v[174:175], s[86:87] op_sel_hi:[1,0]
	v_rcp_f32_e32 v168, v168
	v_rcp_f32_e32 v169, v169
	v_rcp_f32_e32 v170, v170
	v_rcp_f32_e32 v171, v171
	v_rcp_f32_e32 v172, v172
	v_rcp_f32_e32 v173, v173
	v_rcp_f32_e32 v174, v174
	v_rcp_f32_e32 v175, v175
	v_pk_mul_f32 v[168:169], v[130:131], v[168:169]
	v_pk_mul_f32 v[170:171], v[132:133], v[170:171]
	v_pk_mul_f32 v[172:173], v[98:99], v[172:173]
	v_pk_mul_f32 v[174:175], v[100:101], v[174:175]
	v_cvt_pk_bf16_f32 v176, v168, v169
	v_cvt_pk_bf16_f32 v177, v170, v171
	v_cvt_pk_bf16_f32 v178, v172, v173
	v_cvt_pk_bf16_f32 v179, v174, v175
	ds_bpermute_b32 v180, v151, v176
	ds_bpermute_b32 v181, v151, v177
	ds_bpermute_b32 v182, v151, v178
	ds_bpermute_b32 v183, v151, v179
	s_waitcnt lgkmcnt(4)
	global_store_dwordx4 v[138:139], v[164:167], off nt
	s_mov_b64 s[2:3], 0x8000
	v_lshl_add_u64 v[140:141], v[136:137], 0, s[2:3]
	v_pk_mul_f32 v[152:153], v[114:115], s[84:85] op_sel_hi:[1,0]
	v_pk_mul_f32 v[154:155], v[116:117], s[84:85] op_sel_hi:[1,0]
	v_pk_mul_f32 v[156:157], v[82:83], s[84:85] op_sel_hi:[1,0]
	v_pk_mul_f32 v[158:159], v[84:85], s[84:85] op_sel_hi:[1,0]
	v_exp_f32_e32 v152, v152
	v_exp_f32_e32 v153, v153
	v_exp_f32_e32 v154, v154
	v_exp_f32_e32 v155, v155
	v_exp_f32_e32 v156, v156
	v_exp_f32_e32 v157, v157
	v_exp_f32_e32 v158, v158
	v_exp_f32_e32 v159, v159
	v_pk_add_f32 v[152:153], v[152:153], s[86:87] op_sel_hi:[1,0]
	v_pk_add_f32 v[154:155], v[154:155], s[86:87] op_sel_hi:[1,0]
	v_pk_add_f32 v[156:157], v[156:157], s[86:87] op_sel_hi:[1,0]
	v_pk_add_f32 v[158:159], v[158:159], s[86:87] op_sel_hi:[1,0]
	v_rcp_f32_e32 v152, v152
	v_rcp_f32_e32 v153, v153
	v_rcp_f32_e32 v154, v154
	v_rcp_f32_e32 v155, v155
	v_rcp_f32_e32 v156, v156
	v_rcp_f32_e32 v157, v157
	v_rcp_f32_e32 v158, v158
	v_rcp_f32_e32 v159, v159
	v_pk_mul_f32 v[152:153], v[114:115], v[152:153]
	v_pk_mul_f32 v[154:155], v[116:117], v[154:155]
	v_pk_mul_f32 v[156:157], v[82:83], v[156:157]
	v_pk_mul_f32 v[158:159], v[84:85], v[158:159]
	v_cvt_pk_bf16_f32 v160, v152, v153
	v_cvt_pk_bf16_f32 v161, v154, v155
	v_cvt_pk_bf16_f32 v162, v156, v157
	v_cvt_pk_bf16_f32 v163, v158, v159
	ds_bpermute_b32 v164, v151, v160
	ds_bpermute_b32 v165, v151, v161
	ds_bpermute_b32 v166, v151, v162
	ds_bpermute_b32 v167, v151, v163
	s_waitcnt lgkmcnt(4)
	global_store_dwordx4 v[138:139], v[180:183], off offset:256 nt
	v_pk_mul_f32 v[168:169], v[126:127], s[84:85] op_sel_hi:[1,0]
	v_pk_mul_f32 v[170:171], v[128:129], s[84:85] op_sel_hi:[1,0]
	v_pk_mul_f32 v[172:173], v[94:95], s[84:85] op_sel_hi:[1,0]
	v_pk_mul_f32 v[174:175], v[96:97], s[84:85] op_sel_hi:[1,0]
	v_exp_f32_e32 v168, v168
	v_exp_f32_e32 v169, v169
	v_exp_f32_e32 v170, v170
	v_exp_f32_e32 v171, v171
	v_exp_f32_e32 v172, v172
	v_exp_f32_e32 v173, v173
	v_exp_f32_e32 v174, v174
	v_exp_f32_e32 v175, v175
	v_pk_add_f32 v[168:169], v[168:169], s[86:87] op_sel_hi:[1,0]
	v_pk_add_f32 v[170:171], v[170:171], s[86:87] op_sel_hi:[1,0]
	v_pk_add_f32 v[172:173], v[172:173], s[86:87] op_sel_hi:[1,0]
	v_pk_add_f32 v[174:175], v[174:175], s[86:87] op_sel_hi:[1,0]
	v_rcp_f32_e32 v168, v168
	v_rcp_f32_e32 v169, v169
	v_rcp_f32_e32 v170, v170
	v_rcp_f32_e32 v171, v171
	v_rcp_f32_e32 v172, v172
	v_rcp_f32_e32 v173, v173
	v_rcp_f32_e32 v174, v174
	v_rcp_f32_e32 v175, v175
	v_pk_mul_f32 v[168:169], v[126:127], v[168:169]
	v_pk_mul_f32 v[170:171], v[128:129], v[170:171]
	v_pk_mul_f32 v[172:173], v[94:95], v[172:173]
	v_pk_mul_f32 v[174:175], v[96:97], v[174:175]
	v_cvt_pk_bf16_f32 v176, v168, v169
	v_cvt_pk_bf16_f32 v177, v170, v171
	v_cvt_pk_bf16_f32 v178, v172, v173
	v_cvt_pk_bf16_f32 v179, v174, v175
	ds_bpermute_b32 v180, v151, v176
	ds_bpermute_b32 v181, v151, v177
	ds_bpermute_b32 v182, v151, v178
	ds_bpermute_b32 v183, v151, v179
	s_waitcnt lgkmcnt(4)
	global_store_dwordx4 v[140:141], v[164:167], off nt
	s_mov_b64 s[2:3], 0x10000
	v_lshl_add_u64 v[138:139], v[136:137], 0, s[2:3]
	v_pk_mul_f32 v[152:153], v[110:111], s[84:85] op_sel_hi:[1,0]
	v_pk_mul_f32 v[154:155], v[112:113], s[84:85] op_sel_hi:[1,0]
	v_pk_mul_f32 v[156:157], v[78:79], s[84:85] op_sel_hi:[1,0]
	v_pk_mul_f32 v[158:159], v[80:81], s[84:85] op_sel_hi:[1,0]
	v_exp_f32_e32 v152, v152
	v_exp_f32_e32 v153, v153
	v_exp_f32_e32 v154, v154
	v_exp_f32_e32 v155, v155
	v_exp_f32_e32 v156, v156
	v_exp_f32_e32 v157, v157
	v_exp_f32_e32 v158, v158
	v_exp_f32_e32 v159, v159
	v_pk_add_f32 v[152:153], v[152:153], s[86:87] op_sel_hi:[1,0]
	v_pk_add_f32 v[154:155], v[154:155], s[86:87] op_sel_hi:[1,0]
	v_pk_add_f32 v[156:157], v[156:157], s[86:87] op_sel_hi:[1,0]
	v_pk_add_f32 v[158:159], v[158:159], s[86:87] op_sel_hi:[1,0]
	v_rcp_f32_e32 v152, v152
	v_rcp_f32_e32 v153, v153
	v_rcp_f32_e32 v154, v154
	v_rcp_f32_e32 v155, v155
	v_rcp_f32_e32 v156, v156
	v_rcp_f32_e32 v157, v157
	v_rcp_f32_e32 v158, v158
	v_rcp_f32_e32 v159, v159
	v_pk_mul_f32 v[152:153], v[110:111], v[152:153]
	v_pk_mul_f32 v[154:155], v[112:113], v[154:155]
	v_pk_mul_f32 v[156:157], v[78:79], v[156:157]
	v_pk_mul_f32 v[158:159], v[80:81], v[158:159]
	v_cvt_pk_bf16_f32 v160, v152, v153
	v_cvt_pk_bf16_f32 v161, v154, v155
	v_cvt_pk_bf16_f32 v162, v156, v157
	v_cvt_pk_bf16_f32 v163, v158, v159
	ds_bpermute_b32 v164, v151, v160
	ds_bpermute_b32 v165, v151, v161
	ds_bpermute_b32 v166, v151, v162
	ds_bpermute_b32 v167, v151, v163
	s_waitcnt lgkmcnt(4)
	global_store_dwordx4 v[140:141], v[180:183], off offset:256 nt
	v_pk_mul_f32 v[168:169], v[122:123], s[84:85] op_sel_hi:[1,0]
	v_pk_mul_f32 v[170:171], v[124:125], s[84:85] op_sel_hi:[1,0]
	v_pk_mul_f32 v[172:173], v[90:91], s[84:85] op_sel_hi:[1,0]
	v_pk_mul_f32 v[174:175], v[92:93], s[84:85] op_sel_hi:[1,0]
	v_exp_f32_e32 v168, v168
	v_exp_f32_e32 v169, v169
	v_exp_f32_e32 v170, v170
	v_exp_f32_e32 v171, v171
	v_exp_f32_e32 v172, v172
	v_exp_f32_e32 v173, v173
	v_exp_f32_e32 v174, v174
	v_exp_f32_e32 v175, v175
	v_pk_add_f32 v[168:169], v[168:169], s[86:87] op_sel_hi:[1,0]
	v_pk_add_f32 v[170:171], v[170:171], s[86:87] op_sel_hi:[1,0]
	v_pk_add_f32 v[172:173], v[172:173], s[86:87] op_sel_hi:[1,0]
	v_pk_add_f32 v[174:175], v[174:175], s[86:87] op_sel_hi:[1,0]
	v_rcp_f32_e32 v168, v168
	v_rcp_f32_e32 v169, v169
	v_rcp_f32_e32 v170, v170
	v_rcp_f32_e32 v171, v171
	v_rcp_f32_e32 v172, v172
	v_rcp_f32_e32 v173, v173
	v_rcp_f32_e32 v174, v174
	v_rcp_f32_e32 v175, v175
	v_pk_mul_f32 v[168:169], v[122:123], v[168:169]
	v_pk_mul_f32 v[170:171], v[124:125], v[170:171]
	v_pk_mul_f32 v[172:173], v[90:91], v[172:173]
	v_pk_mul_f32 v[174:175], v[92:93], v[174:175]
	v_cvt_pk_bf16_f32 v176, v168, v169
	v_cvt_pk_bf16_f32 v177, v170, v171
	v_cvt_pk_bf16_f32 v178, v172, v173
	v_cvt_pk_bf16_f32 v179, v174, v175
	ds_bpermute_b32 v180, v151, v176
	ds_bpermute_b32 v181, v151, v177
	ds_bpermute_b32 v182, v151, v178
	ds_bpermute_b32 v183, v151, v179
	s_waitcnt lgkmcnt(4)
	global_store_dwordx4 v[138:139], v[164:167], off nt
	s_mov_b64 s[2:3], 0x18000
	v_lshl_add_u64 v[140:141], v[136:137], 0, s[2:3]
	v_pk_mul_f32 v[152:153], v[106:107], s[84:85] op_sel_hi:[1,0]
	v_pk_mul_f32 v[154:155], v[108:109], s[84:85] op_sel_hi:[1,0]
	v_pk_mul_f32 v[156:157], v[74:75], s[84:85] op_sel_hi:[1,0]
	v_pk_mul_f32 v[158:159], v[76:77], s[84:85] op_sel_hi:[1,0]
	v_exp_f32_e32 v152, v152
	v_exp_f32_e32 v153, v153
	v_exp_f32_e32 v154, v154
	v_exp_f32_e32 v155, v155
	v_exp_f32_e32 v156, v156
	v_exp_f32_e32 v157, v157
	v_exp_f32_e32 v158, v158
	v_exp_f32_e32 v159, v159
	v_pk_add_f32 v[152:153], v[152:153], s[86:87] op_sel_hi:[1,0]
	v_pk_add_f32 v[154:155], v[154:155], s[86:87] op_sel_hi:[1,0]
	v_pk_add_f32 v[156:157], v[156:157], s[86:87] op_sel_hi:[1,0]
	v_pk_add_f32 v[158:159], v[158:159], s[86:87] op_sel_hi:[1,0]
	v_rcp_f32_e32 v152, v152
	v_rcp_f32_e32 v153, v153
	v_rcp_f32_e32 v154, v154
	v_rcp_f32_e32 v155, v155
	v_rcp_f32_e32 v156, v156
	v_rcp_f32_e32 v157, v157
	v_rcp_f32_e32 v158, v158
	v_rcp_f32_e32 v159, v159
	v_pk_mul_f32 v[152:153], v[106:107], v[152:153]
	v_pk_mul_f32 v[154:155], v[108:109], v[154:155]
	v_pk_mul_f32 v[156:157], v[74:75], v[156:157]
	v_pk_mul_f32 v[158:159], v[76:77], v[158:159]
	v_cvt_pk_bf16_f32 v160, v152, v153
	v_cvt_pk_bf16_f32 v161, v154, v155
	v_cvt_pk_bf16_f32 v162, v156, v157
	v_cvt_pk_bf16_f32 v163, v158, v159
	ds_bpermute_b32 v164, v151, v160
	ds_bpermute_b32 v165, v151, v161
	ds_bpermute_b32 v166, v151, v162
	ds_bpermute_b32 v167, v151, v163
	s_waitcnt lgkmcnt(4)
	global_store_dwordx4 v[138:139], v[180:183], off offset:256 nt
	v_pk_mul_f32 v[168:169], v[118:119], s[84:85] op_sel_hi:[1,0]
	v_pk_mul_f32 v[170:171], v[120:121], s[84:85] op_sel_hi:[1,0]
	v_pk_mul_f32 v[172:173], v[86:87], s[84:85] op_sel_hi:[1,0]
	v_pk_mul_f32 v[174:175], v[88:89], s[84:85] op_sel_hi:[1,0]
	v_exp_f32_e32 v168, v168
	v_exp_f32_e32 v169, v169
	v_exp_f32_e32 v170, v170
	v_exp_f32_e32 v171, v171
	v_exp_f32_e32 v172, v172
	v_exp_f32_e32 v173, v173
	v_exp_f32_e32 v174, v174
	v_exp_f32_e32 v175, v175
	v_pk_add_f32 v[168:169], v[168:169], s[86:87] op_sel_hi:[1,0]
	v_pk_add_f32 v[170:171], v[170:171], s[86:87] op_sel_hi:[1,0]
	v_pk_add_f32 v[172:173], v[172:173], s[86:87] op_sel_hi:[1,0]
	v_pk_add_f32 v[174:175], v[174:175], s[86:87] op_sel_hi:[1,0]
	v_rcp_f32_e32 v168, v168
	v_rcp_f32_e32 v169, v169
	v_rcp_f32_e32 v170, v170
	v_rcp_f32_e32 v171, v171
	v_rcp_f32_e32 v172, v172
	v_rcp_f32_e32 v173, v173
	v_rcp_f32_e32 v174, v174
	v_rcp_f32_e32 v175, v175
	v_pk_mul_f32 v[168:169], v[118:119], v[168:169]
	v_pk_mul_f32 v[170:171], v[120:121], v[170:171]
	v_pk_mul_f32 v[172:173], v[86:87], v[172:173]
	v_pk_mul_f32 v[174:175], v[88:89], v[174:175]
	v_cvt_pk_bf16_f32 v176, v168, v169
	v_cvt_pk_bf16_f32 v177, v170, v171
	v_cvt_pk_bf16_f32 v178, v172, v173
	v_cvt_pk_bf16_f32 v179, v174, v175
	ds_bpermute_b32 v180, v151, v176
	ds_bpermute_b32 v181, v151, v177
	ds_bpermute_b32 v182, v151, v178
	ds_bpermute_b32 v183, v151, v179
	s_waitcnt lgkmcnt(4)
	global_store_dwordx4 v[140:141], v[164:167], off nt
	s_mov_b64 s[2:3], 0x40000
	v_lshl_add_u64 v[138:139], v[136:137], 0, s[2:3]
	v_pk_mul_f32 v[152:153], v[38:39], s[84:85] op_sel_hi:[1,0]
	v_pk_mul_f32 v[154:155], v[40:41], s[84:85] op_sel_hi:[1,0]
	v_pk_mul_f32 v[156:157], v[6:7], s[84:85] op_sel_hi:[1,0]
	v_pk_mul_f32 v[158:159], v[8:9], s[84:85] op_sel_hi:[1,0]
	v_exp_f32_e32 v152, v152
	v_exp_f32_e32 v153, v153
	v_exp_f32_e32 v154, v154
	v_exp_f32_e32 v155, v155
	v_exp_f32_e32 v156, v156
	v_exp_f32_e32 v157, v157
	v_exp_f32_e32 v158, v158
	v_exp_f32_e32 v159, v159
	v_pk_add_f32 v[152:153], v[152:153], s[86:87] op_sel_hi:[1,0]
	v_pk_add_f32 v[154:155], v[154:155], s[86:87] op_sel_hi:[1,0]
	v_pk_add_f32 v[156:157], v[156:157], s[86:87] op_sel_hi:[1,0]
	v_pk_add_f32 v[158:159], v[158:159], s[86:87] op_sel_hi:[1,0]
	v_rcp_f32_e32 v152, v152
	v_rcp_f32_e32 v153, v153
	v_rcp_f32_e32 v154, v154
	v_rcp_f32_e32 v155, v155
	v_rcp_f32_e32 v156, v156
	v_rcp_f32_e32 v157, v157
	v_rcp_f32_e32 v158, v158
	v_rcp_f32_e32 v159, v159
	v_pk_mul_f32 v[152:153], v[38:39], v[152:153]
	v_pk_mul_f32 v[154:155], v[40:41], v[154:155]
	v_pk_mul_f32 v[156:157], v[6:7], v[156:157]
	v_pk_mul_f32 v[158:159], v[8:9], v[158:159]
	v_cvt_pk_bf16_f32 v160, v152, v153
	v_cvt_pk_bf16_f32 v161, v154, v155
	v_cvt_pk_bf16_f32 v162, v156, v157
	v_cvt_pk_bf16_f32 v163, v158, v159
	ds_bpermute_b32 v164, v151, v160
	ds_bpermute_b32 v165, v151, v161
	ds_bpermute_b32 v166, v151, v162
	ds_bpermute_b32 v167, v151, v163
	s_waitcnt lgkmcnt(4)
	global_store_dwordx4 v[140:141], v[180:183], off offset:256 nt
	v_pk_mul_f32 v[168:169], v[62:63], s[84:85] op_sel_hi:[1,0]
	v_pk_mul_f32 v[170:171], v[64:65], s[84:85] op_sel_hi:[1,0]
	v_pk_mul_f32 v[172:173], v[30:31], s[84:85] op_sel_hi:[1,0]
	v_pk_mul_f32 v[174:175], v[32:33], s[84:85] op_sel_hi:[1,0]
	v_exp_f32_e32 v168, v168
	v_exp_f32_e32 v169, v169
	v_exp_f32_e32 v170, v170
	v_exp_f32_e32 v171, v171
	v_exp_f32_e32 v172, v172
	v_exp_f32_e32 v173, v173
	v_exp_f32_e32 v174, v174
	v_exp_f32_e32 v175, v175
	v_pk_add_f32 v[168:169], v[168:169], s[86:87] op_sel_hi:[1,0]
	v_pk_add_f32 v[170:171], v[170:171], s[86:87] op_sel_hi:[1,0]
	v_pk_add_f32 v[172:173], v[172:173], s[86:87] op_sel_hi:[1,0]
	v_pk_add_f32 v[174:175], v[174:175], s[86:87] op_sel_hi:[1,0]
	v_rcp_f32_e32 v168, v168
	v_rcp_f32_e32 v169, v169
	v_rcp_f32_e32 v170, v170
	v_rcp_f32_e32 v171, v171
	v_rcp_f32_e32 v172, v172
	v_rcp_f32_e32 v173, v173
	v_rcp_f32_e32 v174, v174
	v_rcp_f32_e32 v175, v175
	v_pk_mul_f32 v[168:169], v[62:63], v[168:169]
	v_pk_mul_f32 v[170:171], v[64:65], v[170:171]
	v_pk_mul_f32 v[172:173], v[30:31], v[172:173]
	v_pk_mul_f32 v[174:175], v[32:33], v[174:175]
	v_cvt_pk_bf16_f32 v176, v168, v169
	v_cvt_pk_bf16_f32 v177, v170, v171
	v_cvt_pk_bf16_f32 v178, v172, v173
	v_cvt_pk_bf16_f32 v179, v174, v175
	ds_bpermute_b32 v180, v151, v176
	ds_bpermute_b32 v181, v151, v177
	ds_bpermute_b32 v182, v151, v178
	ds_bpermute_b32 v183, v151, v179
	s_waitcnt lgkmcnt(4)
	global_store_dwordx4 v[138:139], v[164:167], off nt
	s_mov_b64 s[2:3], 0x48000
	v_lshl_add_u64 v[140:141], v[136:137], 0, s[2:3]
	v_pk_mul_f32 v[152:153], v[50:51], s[84:85] op_sel_hi:[1,0]
	v_pk_mul_f32 v[154:155], v[52:53], s[84:85] op_sel_hi:[1,0]
	v_pk_mul_f32 v[156:157], v[18:19], s[84:85] op_sel_hi:[1,0]
	v_pk_mul_f32 v[158:159], v[20:21], s[84:85] op_sel_hi:[1,0]
	v_exp_f32_e32 v152, v152
	v_exp_f32_e32 v153, v153
	v_exp_f32_e32 v154, v154
	v_exp_f32_e32 v155, v155
	v_exp_f32_e32 v156, v156
	v_exp_f32_e32 v157, v157
	v_exp_f32_e32 v158, v158
	v_exp_f32_e32 v159, v159
	v_pk_add_f32 v[152:153], v[152:153], s[86:87] op_sel_hi:[1,0]
	v_pk_add_f32 v[154:155], v[154:155], s[86:87] op_sel_hi:[1,0]
	v_pk_add_f32 v[156:157], v[156:157], s[86:87] op_sel_hi:[1,0]
	v_pk_add_f32 v[158:159], v[158:159], s[86:87] op_sel_hi:[1,0]
	v_rcp_f32_e32 v152, v152
	v_rcp_f32_e32 v153, v153
	v_rcp_f32_e32 v154, v154
	v_rcp_f32_e32 v155, v155
	v_rcp_f32_e32 v156, v156
	v_rcp_f32_e32 v157, v157
	v_rcp_f32_e32 v158, v158
	v_rcp_f32_e32 v159, v159
	v_pk_mul_f32 v[152:153], v[50:51], v[152:153]
	v_pk_mul_f32 v[154:155], v[52:53], v[154:155]
	v_pk_mul_f32 v[156:157], v[18:19], v[156:157]
	v_pk_mul_f32 v[158:159], v[20:21], v[158:159]
	v_cvt_pk_bf16_f32 v160, v152, v153
	v_cvt_pk_bf16_f32 v161, v154, v155
	v_cvt_pk_bf16_f32 v162, v156, v157
	v_cvt_pk_bf16_f32 v163, v158, v159
	ds_bpermute_b32 v164, v151, v160
	ds_bpermute_b32 v165, v151, v161
	ds_bpermute_b32 v166, v151, v162
	ds_bpermute_b32 v167, v151, v163
	s_waitcnt lgkmcnt(4)
	global_store_dwordx4 v[138:139], v[180:183], off offset:256 nt
	v_pk_mul_f32 v[168:169], v[66:67], s[84:85] op_sel_hi:[1,0]
	v_pk_mul_f32 v[170:171], v[68:69], s[84:85] op_sel_hi:[1,0]
	v_pk_mul_f32 v[172:173], v[34:35], s[84:85] op_sel_hi:[1,0]
	v_pk_mul_f32 v[174:175], v[36:37], s[84:85] op_sel_hi:[1,0]
	v_exp_f32_e32 v168, v168
	v_exp_f32_e32 v169, v169
	v_exp_f32_e32 v170, v170
	v_exp_f32_e32 v171, v171
	v_exp_f32_e32 v172, v172
	v_exp_f32_e32 v173, v173
	v_exp_f32_e32 v174, v174
	v_exp_f32_e32 v175, v175
	v_pk_add_f32 v[168:169], v[168:169], s[86:87] op_sel_hi:[1,0]
	v_pk_add_f32 v[170:171], v[170:171], s[86:87] op_sel_hi:[1,0]
	v_pk_add_f32 v[172:173], v[172:173], s[86:87] op_sel_hi:[1,0]
	v_pk_add_f32 v[174:175], v[174:175], s[86:87] op_sel_hi:[1,0]
	v_rcp_f32_e32 v168, v168
	v_rcp_f32_e32 v169, v169
	v_rcp_f32_e32 v170, v170
	v_rcp_f32_e32 v171, v171
	v_rcp_f32_e32 v172, v172
	v_rcp_f32_e32 v173, v173
	v_rcp_f32_e32 v174, v174
	v_rcp_f32_e32 v175, v175
	v_pk_mul_f32 v[168:169], v[66:67], v[168:169]
	v_pk_mul_f32 v[170:171], v[68:69], v[170:171]
	v_pk_mul_f32 v[172:173], v[34:35], v[172:173]
	v_pk_mul_f32 v[174:175], v[36:37], v[174:175]
	v_cvt_pk_bf16_f32 v176, v168, v169
	v_cvt_pk_bf16_f32 v177, v170, v171
	v_cvt_pk_bf16_f32 v178, v172, v173
	v_cvt_pk_bf16_f32 v179, v174, v175
	ds_bpermute_b32 v180, v151, v176
	ds_bpermute_b32 v181, v151, v177
	ds_bpermute_b32 v182, v151, v178
	ds_bpermute_b32 v183, v151, v179
	s_waitcnt lgkmcnt(4)
	global_store_dwordx4 v[140:141], v[164:167], off nt
	s_mov_b64 s[2:3], 0x50000
	v_lshl_add_u64 v[138:139], v[136:137], 0, s[2:3]
	v_pk_mul_f32 v[152:153], v[46:47], s[84:85] op_sel_hi:[1,0]
	v_pk_mul_f32 v[154:155], v[48:49], s[84:85] op_sel_hi:[1,0]
	v_pk_mul_f32 v[156:157], v[14:15], s[84:85] op_sel_hi:[1,0]
	v_pk_mul_f32 v[158:159], v[16:17], s[84:85] op_sel_hi:[1,0]
	v_exp_f32_e32 v152, v152
	v_exp_f32_e32 v153, v153
	v_exp_f32_e32 v154, v154
	v_exp_f32_e32 v155, v155
	v_exp_f32_e32 v156, v156
	v_exp_f32_e32 v157, v157
	v_exp_f32_e32 v158, v158
	v_exp_f32_e32 v159, v159
	v_pk_add_f32 v[152:153], v[152:153], s[86:87] op_sel_hi:[1,0]
	v_pk_add_f32 v[154:155], v[154:155], s[86:87] op_sel_hi:[1,0]
	v_pk_add_f32 v[156:157], v[156:157], s[86:87] op_sel_hi:[1,0]
	v_pk_add_f32 v[158:159], v[158:159], s[86:87] op_sel_hi:[1,0]
	v_rcp_f32_e32 v152, v152
	v_rcp_f32_e32 v153, v153
	v_rcp_f32_e32 v154, v154
	v_rcp_f32_e32 v155, v155
	v_rcp_f32_e32 v156, v156
	v_rcp_f32_e32 v157, v157
	v_rcp_f32_e32 v158, v158
	v_rcp_f32_e32 v159, v159
	v_pk_mul_f32 v[152:153], v[46:47], v[152:153]
	v_pk_mul_f32 v[154:155], v[48:49], v[154:155]
	v_pk_mul_f32 v[156:157], v[14:15], v[156:157]
	v_pk_mul_f32 v[158:159], v[16:17], v[158:159]
	v_cvt_pk_bf16_f32 v160, v152, v153
	v_cvt_pk_bf16_f32 v161, v154, v155
	v_cvt_pk_bf16_f32 v162, v156, v157
	v_cvt_pk_bf16_f32 v163, v158, v159
	ds_bpermute_b32 v164, v151, v160
	ds_bpermute_b32 v165, v151, v161
	ds_bpermute_b32 v166, v151, v162
	ds_bpermute_b32 v167, v151, v163
	s_waitcnt lgkmcnt(4)
	global_store_dwordx4 v[140:141], v[180:183], off offset:256 nt
	v_pk_mul_f32 v[168:169], v[58:59], s[84:85] op_sel_hi:[1,0]
	v_pk_mul_f32 v[170:171], v[60:61], s[84:85] op_sel_hi:[1,0]
	v_pk_mul_f32 v[172:173], v[26:27], s[84:85] op_sel_hi:[1,0]
	v_pk_mul_f32 v[174:175], v[28:29], s[84:85] op_sel_hi:[1,0]
	v_exp_f32_e32 v168, v168
	v_exp_f32_e32 v169, v169
	v_exp_f32_e32 v170, v170
	v_exp_f32_e32 v171, v171
	v_exp_f32_e32 v172, v172
	v_exp_f32_e32 v173, v173
	v_exp_f32_e32 v174, v174
	v_exp_f32_e32 v175, v175
	v_pk_add_f32 v[168:169], v[168:169], s[86:87] op_sel_hi:[1,0]
	v_pk_add_f32 v[170:171], v[170:171], s[86:87] op_sel_hi:[1,0]
	v_pk_add_f32 v[172:173], v[172:173], s[86:87] op_sel_hi:[1,0]
	v_pk_add_f32 v[174:175], v[174:175], s[86:87] op_sel_hi:[1,0]
	v_rcp_f32_e32 v168, v168
	v_rcp_f32_e32 v169, v169
	v_rcp_f32_e32 v170, v170
	v_rcp_f32_e32 v171, v171
	v_rcp_f32_e32 v172, v172
	v_rcp_f32_e32 v173, v173
	v_rcp_f32_e32 v174, v174
	v_rcp_f32_e32 v175, v175
	v_pk_mul_f32 v[168:169], v[58:59], v[168:169]
	v_pk_mul_f32 v[170:171], v[60:61], v[170:171]
	v_pk_mul_f32 v[172:173], v[26:27], v[172:173]
	v_pk_mul_f32 v[174:175], v[28:29], v[174:175]
	v_cvt_pk_bf16_f32 v176, v168, v169
	v_cvt_pk_bf16_f32 v177, v170, v171
	v_cvt_pk_bf16_f32 v178, v172, v173
	v_cvt_pk_bf16_f32 v179, v174, v175
	ds_bpermute_b32 v180, v151, v176
	ds_bpermute_b32 v181, v151, v177
	ds_bpermute_b32 v182, v151, v178
	ds_bpermute_b32 v183, v151, v179
	s_waitcnt lgkmcnt(4)
	global_store_dwordx4 v[138:139], v[164:167], off nt
	s_mov_b64 s[2:3], 0x58000
	v_lshl_add_u64 v[140:141], v[136:137], 0, s[2:3]
	v_pk_mul_f32 v[152:153], v[42:43], s[84:85] op_sel_hi:[1,0]
	v_pk_mul_f32 v[154:155], v[44:45], s[84:85] op_sel_hi:[1,0]
	v_pk_mul_f32 v[156:157], v[10:11], s[84:85] op_sel_hi:[1,0]
	v_pk_mul_f32 v[158:159], v[12:13], s[84:85] op_sel_hi:[1,0]
	v_exp_f32_e32 v152, v152
	v_exp_f32_e32 v153, v153
	v_exp_f32_e32 v154, v154
	v_exp_f32_e32 v155, v155
	v_exp_f32_e32 v156, v156
	v_exp_f32_e32 v157, v157
	v_exp_f32_e32 v158, v158
	v_exp_f32_e32 v159, v159
	v_pk_add_f32 v[152:153], v[152:153], s[86:87] op_sel_hi:[1,0]
	v_pk_add_f32 v[154:155], v[154:155], s[86:87] op_sel_hi:[1,0]
	v_pk_add_f32 v[156:157], v[156:157], s[86:87] op_sel_hi:[1,0]
	v_pk_add_f32 v[158:159], v[158:159], s[86:87] op_sel_hi:[1,0]
	v_rcp_f32_e32 v152, v152
	v_rcp_f32_e32 v153, v153
	v_rcp_f32_e32 v154, v154
	v_rcp_f32_e32 v155, v155
	v_rcp_f32_e32 v156, v156
	v_rcp_f32_e32 v157, v157
	v_rcp_f32_e32 v158, v158
	v_rcp_f32_e32 v159, v159
	v_pk_mul_f32 v[152:153], v[42:43], v[152:153]
	v_pk_mul_f32 v[154:155], v[44:45], v[154:155]
	v_pk_mul_f32 v[156:157], v[10:11], v[156:157]
	v_pk_mul_f32 v[158:159], v[12:13], v[158:159]
	v_cvt_pk_bf16_f32 v160, v152, v153
	v_cvt_pk_bf16_f32 v161, v154, v155
	v_cvt_pk_bf16_f32 v162, v156, v157
	v_cvt_pk_bf16_f32 v163, v158, v159
	ds_bpermute_b32 v164, v151, v160
	ds_bpermute_b32 v165, v151, v161
	ds_bpermute_b32 v166, v151, v162
	ds_bpermute_b32 v167, v151, v163
	s_waitcnt lgkmcnt(4)
	global_store_dwordx4 v[138:139], v[180:183], off offset:256 nt
	v_pk_mul_f32 v[168:169], v[54:55], s[84:85] op_sel_hi:[1,0]
	v_pk_mul_f32 v[170:171], v[56:57], s[84:85] op_sel_hi:[1,0]
	v_pk_mul_f32 v[172:173], v[22:23], s[84:85] op_sel_hi:[1,0]
	v_pk_mul_f32 v[174:175], v[24:25], s[84:85] op_sel_hi:[1,0]
	v_exp_f32_e32 v168, v168
	v_exp_f32_e32 v169, v169
	v_exp_f32_e32 v170, v170
	v_exp_f32_e32 v171, v171
	v_exp_f32_e32 v172, v172
	v_exp_f32_e32 v173, v173
	v_exp_f32_e32 v174, v174
	v_exp_f32_e32 v175, v175
	v_pk_add_f32 v[168:169], v[168:169], s[86:87] op_sel_hi:[1,0]
	v_pk_add_f32 v[170:171], v[170:171], s[86:87] op_sel_hi:[1,0]
	v_pk_add_f32 v[172:173], v[172:173], s[86:87] op_sel_hi:[1,0]
	v_pk_add_f32 v[174:175], v[174:175], s[86:87] op_sel_hi:[1,0]
	v_rcp_f32_e32 v168, v168
	v_rcp_f32_e32 v169, v169
	v_rcp_f32_e32 v170, v170
	v_rcp_f32_e32 v171, v171
	v_rcp_f32_e32 v172, v172
	v_rcp_f32_e32 v173, v173
	v_rcp_f32_e32 v174, v174
	v_rcp_f32_e32 v175, v175
	v_pk_mul_f32 v[168:169], v[54:55], v[168:169]
	v_pk_mul_f32 v[170:171], v[56:57], v[170:171]
	v_pk_mul_f32 v[172:173], v[22:23], v[172:173]
	v_pk_mul_f32 v[174:175], v[24:25], v[174:175]
	v_cvt_pk_bf16_f32 v176, v168, v169
	v_cvt_pk_bf16_f32 v177, v170, v171
	v_cvt_pk_bf16_f32 v178, v172, v173
	v_cvt_pk_bf16_f32 v179, v174, v175
	ds_bpermute_b32 v180, v151, v176
	ds_bpermute_b32 v181, v151, v177
	ds_bpermute_b32 v182, v151, v178
	ds_bpermute_b32 v183, v151, v179
	s_waitcnt lgkmcnt(4)
	global_store_dwordx4 v[140:141], v[164:167], off nt
	s_waitcnt lgkmcnt(0)
	global_store_dwordx4 v[140:141], v[180:183], off offset:256 nt
	s_branch .LBB0_126

.LBB0_156:
	s_andn2_b64 vcc, exec, s[76:77]
	s_cbranch_vccnz .LBB0_158
	v_lshl_add_u32 v135, v150, 4, v3
	v_and_b32_e32 v134, 15, v3
	v_and_b32_e32 v137, 3, v3
	v_sub_u32_e32 v134, v5, v134
	v_ashrrev_i32_e32 v136, 2, v135
	v_lshlrev_b32_e32 v138, 3, v137
	v_lshlrev_b32_e32 v137, 6, v137
	v_add_u32_e32 v134, v136, v134
	v_ashrrev_i32_e32 v136, 1, v135
	v_and_or_b32 v151, v135, -4, v137
	s_lshl_b32 s0, s72, 8
	s_addk_i32 s0, 0xf400
	v_and_b32_e32 v136, -8, v136
	v_add3_u32 v138, s0, v4, v138
	v_sub_u32_e32 v136, v138, v136
	v_ashrrev_i32_e32 v137, 31, v136
	v_ashrrev_i32_e32 v135, 31, v134
	v_lshlrev_b64 v[134:135], 11, v[134:135]
	v_lshl_add_u64 v[136:137], v[136:137], 1, s[28:29]
	v_lshl_add_u64 v[136:137], v[136:137], 0, v[134:135]
	s_branch .Lsilu_body
